# FFN out-projection tile order 4 row tiles x 8 column tiles per XCD round; first seam uses the XCD barrier; rows_to_bf16 and final norm loads batched
# speedup vs baseline: 1.0206x; 1.0133x over previous
;     __device__ bool next(int i, Unit& u) const {
;         const long L = (long)i * G + c; if (L >= nwg) return false;
;         int wgid = (int)L; { const int q = nwg / NXCD, r = nwg % NXCD, xcd = wgid % NXCD, off = wgid / NXCD; wgid = (xcd < r ? xcd * (q + 1) : r * (q + 1) + (xcd - r) * q) + off; }
;         const int nig = WGM * nN, gid = wgid / nig, fm = gid * WGM, gsz = (nM - fm) < WGM ? (nM - fm) : WGM;
;         u.pm = fm + ((wgid % nig) % gsz); u.pn = (wgid % nig) / gsz; return true;
;     }
.LBB0_548:
	s_ashr_i32 s4, s7, 3
	s_add_i32 s4, s9, s4
	s_ashr_i32 s5, s4, 31
	s_lshr_b32 s5, s5, 27
	s_add_i32 s5, s4, s5
	s_ashr_i32 s7, s5, 5
	s_and_b32 s5, s5, 0xffe0
	s_sub_i32 s4, s4, s5
	s_bfe_i32 s5, s4, 0x80000
	s_bfe_u32 s5, s5, 0x2000c
	s_add_i32 s5, s4, s5
	s_bfe_i32 s8, s5, 0x80000
	s_and_b32 s5, s5, 0xfc
	s_sub_i32 s4, s4, s5
	s_lshl_b32 s7, s7, 2
	s_sext_i32_i16 s8, s8
	s_sext_i32_i8 s4, s4
	s_add_i32 s83, s7, s4
	s_ashr_i32 s88, s8, 2

;     __device__ bool next(int i, Unit& u) const {
;         const long L = (long)i * G + c; if (L >= nwg) return false;
;         int wgid = (int)L; { const int q = nwg / NXCD, r = nwg % NXCD, xcd = wgid % NXCD, off = wgid / NXCD; wgid = (xcd < r ? xcd * (q + 1) : r * (q + 1) + (xcd - r) * q) + off; }
;         const int nig = WGM * nN, gid = wgid / nig, fm = gid * WGM, gsz = (nM - fm) < WGM ? (nM - fm) : WGM;
;         u.pm = fm + ((wgid % nig) % gsz); u.pn = (wgid % nig) / gsz; return true;
;     }
.LBB0_560:
	s_ashr_i32 s2, s6, 3
	s_add_i32 s2, s24, s2
	s_ashr_i32 s3, s2, 31
	s_lshr_b32 s3, s3, 27
	s_add_i32 s3, s2, s3
	s_ashr_i32 s6, s3, 5
	s_lshl_b32 s6, s6, 2
	s_sub_i32 s7, 64, s6
	s_min_i32 s7, s7, 4
	s_abs_i32 s24, s7
	v_cvt_f32_u32_e32 v0, s24
	s_sub_i32 s30, 0, s24
	s_andn2_b32 s3, s3, 31
	s_sub_i32 s2, s2, s3
	v_rcp_iflag_f32_e32 v0, v0
	s_abs_i32 s3, s2
	s_xor_b32 s25, s2, s7
	s_ashr_i32 s25, s25, 31
	v_mul_f32_e32 v0, 0x4f7ffffe, v0
	v_cvt_u32_f32_e32 v0, v0
	s_nop 0
	v_readfirstlane_b32 s31, v0
	s_mul_i32 s30, s30, s31
	s_mul_hi_u32 s30, s31, s30
	s_add_i32 s31, s31, s30
	s_mul_hi_u32 s30, s3, s31
	s_mul_i32 s31, s30, s24
	s_sub_i32 s3, s3, s31
	s_add_i32 s45, s30, 1
	s_sub_i32 s31, s3, s24
	s_cmp_ge_u32 s3, s24
	s_cselect_b32 s30, s45, s30
	s_cselect_b32 s3, s31, s3
	s_add_i32 s31, s30, 1
	s_cmp_ge_u32 s3, s24
	s_cselect_b32 s3, s31, s30
	s_xor_b32 s3, s3, s25
	s_sub_i32 s45, s3, s25
	s_mul_i32 s3, s45, s7
	s_sub_i32 s2, s2, s3
	s_add_i32 s82, s6, s2

; __device__ __forceinline__ unsigned cvt_pk_bf16(float lo, float hi) { const f32x2_t v = {lo, hi}; const bf16x2_t b = __builtin_convertvector(v, bf16x2_t); return __builtin_bit_cast(unsigned, b); }
; __device__ __forceinline__ unsigned cvt_pk_f16(float lo, float hi) { const f32x2 v = {lo, hi}; const h16x2_t h = __builtin_convertvector(v, h16x2_t); return __builtin_bit_cast(unsigned, h); }
; __device__ __forceinline__ u64 ssq_fix(float s) { return (u64)__float2ull_rn(s * 16777216.0f); }
; __device__ __forceinline__ void rows_to_bf16(const float* X, bf16_t* XB, bf16_t* X16, u64* ssq, int rows, int gw, int nw) {
;     int tid_ = threadIdx.x; asm volatile("" : "+v"(tid_)); asm volatile("" : "+v"(gw));
;     const int lane = tid_ & 63;
;     for (int r = gw; r < rows; r += nw) {
;         const float* xr = X + (size_t)r * D; bf16_t* br = XB + (size_t)r * D; float ss = 0.f;
; #pragma unroll
;         for (int i = 0; i < 8; ++i) {
;             const f32x4 v = *(const f32x4*)(xr + (i * 64 + lane) * 4);
;             ss += v[0] * v[0] + v[1] * v[1] + v[2] * v[2] + v[3] * v[3];
;             u32x2 w; w.x = cvt_pk_bf16(v[0], v[1]); w.y = cvt_pk_bf16(v[2], v[3]);
;             *(u32x2*)(br + (i * 64 + lane) * 4) = w;
;             if (X16) { u32x2 hq; hq.x = cvt_pk_f16(v[0], v[1]); hq.y = cvt_pk_f16(v[2], v[3]); *(u32x2*)(X16 + (size_t)r * D + (i * 64 + lane) * 4) = hq; }
;         }
;         ss = wave_sum(ss);
;         if (lane == 0) ssq[r] = ssq_fix(ss);
;     }
.LBB0_953:
	s_waitcnt lgkmcnt(0)
	global_load_dwordx4 v[22:25], v[8:9], off offset:-4096
	global_load_dwordx4 v[58:61], v[8:9], off offset:-3072
	global_load_dwordx4 v[62:65], v[8:9], off offset:-2048
	global_load_dwordx4 v[66:69], v[8:9], off offset:-1024
	global_load_dwordx4 v[70:73], v[8:9], off
	global_load_dwordx4 v[74:77], v[8:9], off offset:1024
	global_load_dwordx4 v[78:81], v[8:9], off offset:2048
	global_load_dwordx4 v[82:85], v[8:9], off offset:3072
	v_lshl_add_u64 v[26:27], s[22:23], 0, v[6:7]
	s_mov_b32 s2, 0xda29000
	s_waitcnt vmcnt(19)
	v_add_co_u32_e32 v54, vcc, s2, v26
	s_mov_b32 s2, 0x367a9000
	s_nop 0
	v_addc_co_u32_e32 v55, vcc, 0, v27, vcc
	s_waitcnt vmcnt(18)
	v_add_co_u32_e32 v56, vcc, s2, v26
	s_waitcnt vmcnt(7)
	v_cvt_pk_bf16_f32 v26, v22, v23
	v_addc_co_u32_e32 v57, vcc, 0, v27, vcc
	v_cvt_pk_bf16_f32 v27, v24, v25
	v_cvt_pk_f16_f32 v28, v22, v23
	v_cvt_pk_f16_f32 v29, v24, v25
	global_store_dwordx2 v[54:55], v[26:27], off
	global_store_dwordx2 v[56:57], v[28:29], off
	s_waitcnt vmcnt(8)
	s_nop 1
	v_mov_b64_e32 v[26:27], v[58:59]
	v_mov_b64_e32 v[28:29], v[60:61]
	v_mul_f32_e32 v3, v23, v23
	v_fmac_f32_e32 v3, v22, v22
	v_fmac_f32_e32 v3, v24, v24
	v_fmac_f32_e32 v3, v25, v25
	v_cvt_pk_bf16_f32 v30, v26, v27
	v_cvt_pk_bf16_f32 v31, v28, v29
	v_cvt_pk_f16_f32 v32, v26, v27
	v_cvt_pk_f16_f32 v33, v28, v29
	global_store_dwordx2 v[54:55], v[30:31], off offset:512
	global_store_dwordx2 v[56:57], v[32:33], off offset:512
	s_waitcnt vmcnt(9)
	s_nop 1
	v_mov_b64_e32 v[30:31], v[62:63]
	v_mov_b64_e32 v[32:33], v[64:65]
	v_mul_f32_e32 v22, v27, v27
	v_fmac_f32_e32 v22, v26, v26
	v_fmac_f32_e32 v22, v28, v28
	v_fmac_f32_e32 v22, v29, v29
	v_add_f32_e32 v3, v3, v22
	v_cvt_pk_bf16_f32 v34, v30, v31
	v_cvt_pk_bf16_f32 v35, v32, v33
	v_cvt_pk_f16_f32 v36, v30, v31
	v_cvt_pk_f16_f32 v37, v32, v33
	global_store_dwordx2 v[54:55], v[34:35], off offset:1024
	global_store_dwordx2 v[56:57], v[36:37], off offset:1024
	s_waitcnt vmcnt(10)
	s_nop 1
	v_mov_b64_e32 v[34:35], v[66:67]
	v_mov_b64_e32 v[36:37], v[68:69]
	v_mul_f32_e32 v22, v31, v31
	v_fmac_f32_e32 v22, v30, v30
	v_fmac_f32_e32 v22, v32, v32
	v_fmac_f32_e32 v22, v33, v33
	v_add_f32_e32 v3, v3, v22
	v_cvt_pk_bf16_f32 v38, v34, v35
	v_cvt_pk_bf16_f32 v39, v36, v37
	v_cvt_pk_f16_f32 v40, v34, v35
	v_cvt_pk_f16_f32 v41, v36, v37
	global_store_dwordx2 v[54:55], v[38:39], off offset:1536
	global_store_dwordx2 v[56:57], v[40:41], off offset:1536
	s_waitcnt vmcnt(11)
	s_nop 1
	v_mov_b64_e32 v[38:39], v[70:71]
	v_mov_b64_e32 v[40:41], v[72:73]
	v_mul_f32_e32 v22, v35, v35
	v_fmac_f32_e32 v22, v34, v34
	v_fmac_f32_e32 v22, v36, v36
	v_fmac_f32_e32 v22, v37, v37
	v_add_f32_e32 v3, v3, v22
	v_cvt_pk_bf16_f32 v42, v38, v39
	v_cvt_pk_bf16_f32 v43, v40, v41
	v_cvt_pk_f16_f32 v44, v38, v39
	v_cvt_pk_f16_f32 v45, v40, v41
	global_store_dwordx2 v[54:55], v[42:43], off offset:2048
	global_store_dwordx2 v[56:57], v[44:45], off offset:2048
	s_waitcnt vmcnt(12)
	s_nop 1
	v_mov_b64_e32 v[42:43], v[74:75]
	v_mov_b64_e32 v[44:45], v[76:77]
	v_mul_f32_e32 v22, v39, v39
	v_fmac_f32_e32 v22, v38, v38
	v_fmac_f32_e32 v22, v40, v40
	v_fmac_f32_e32 v22, v41, v41
	v_add_f32_e32 v3, v3, v22
	v_cvt_pk_bf16_f32 v46, v42, v43
	v_cvt_pk_bf16_f32 v47, v44, v45
	v_cvt_pk_f16_f32 v48, v42, v43
	v_cvt_pk_f16_f32 v49, v44, v45
	global_store_dwordx2 v[54:55], v[46:47], off offset:2560
	global_store_dwordx2 v[56:57], v[48:49], off offset:2560
	s_waitcnt vmcnt(13)
	s_nop 1
	v_mov_b64_e32 v[46:47], v[78:79]
	v_mov_b64_e32 v[48:49], v[80:81]
	v_mul_f32_e32 v22, v43, v43
	v_fmac_f32_e32 v22, v42, v42
	v_fmac_f32_e32 v22, v44, v44
	v_fmac_f32_e32 v22, v45, v45
	v_add_f32_e32 v3, v3, v22
	v_cvt_pk_bf16_f32 v50, v46, v47
	v_cvt_pk_bf16_f32 v51, v48, v49
	v_cvt_pk_f16_f32 v52, v46, v47
	v_cvt_pk_f16_f32 v53, v48, v49
	global_store_dwordx2 v[54:55], v[50:51], off offset:3072
	global_store_dwordx2 v[56:57], v[52:53], off offset:3072
	s_waitcnt vmcnt(14)
	s_nop 1
	v_mov_b64_e32 v[50:51], v[82:83]
	v_mov_b64_e32 v[52:53], v[84:85]
	v_mul_f32_e32 v22, v47, v47
	v_fmac_f32_e32 v22, v46, v46
	v_fmac_f32_e32 v22, v48, v48
	v_fmac_f32_e32 v22, v49, v49
	v_add_f32_e32 v3, v3, v22
	v_mul_f32_e32 v22, v51, v51
	v_fmac_f32_e32 v22, v50, v50
	v_fmac_f32_e32 v22, v52, v52
	v_fmac_f32_e32 v22, v53, v53
	v_add_f32_e32 v3, v3, v22
	ds_bpermute_b32 v22, v16, v3
	v_cvt_pk_bf16_f32 v24, v50, v51
	v_cvt_pk_bf16_f32 v25, v52, v53
	global_store_dwordx2 v[54:55], v[24:25], off offset:3584
	v_cvt_pk_f16_f32 v24, v50, v51
	s_waitcnt lgkmcnt(0)
	v_add_f32_e32 v3, v3, v22
	ds_bpermute_b32 v22, v17, v3
	v_cvt_pk_f16_f32 v25, v52, v53
	global_store_dwordx2 v[56:57], v[24:25], off offset:3584
	s_waitcnt lgkmcnt(0)
	v_add_f32_e32 v3, v3, v22
	ds_bpermute_b32 v22, v18, v3
	s_waitcnt lgkmcnt(0)
	v_add_f32_e32 v3, v3, v22
	ds_bpermute_b32 v22, v19, v3
	s_waitcnt lgkmcnt(0)
	v_add_f32_e32 v3, v3, v22
	ds_bpermute_b32 v22, v20, v3
	s_waitcnt lgkmcnt(0)
	v_add_f32_e32 v3, v3, v22
	ds_bpermute_b32 v22, v21, v3
	s_and_saveexec_b64 s[2:3], s[4:5]
	s_cbranch_execz .LBB0_952
	s_waitcnt lgkmcnt(0)
	v_add_f32_e32 v3, v3, v22
	v_mul_f32_e32 v3, 0x4b800000, v3
	v_rndne_f32_e32 v3, v3
	v_mul_f32_e32 v22, 0x2f800000, v3
	v_floor_f32_e32 v23, v22
	v_fmac_f32_e32 v3, 0xcf800000, v23
	v_cvt_u32_f32_e32 v22, v3
	v_cvt_u32_f32_e32 v23, v23
	v_lshl_add_u64 v[24:25], s[22:23], 0, v[4:5]
	global_store_dwordx2 v[24:25], v[22:23], off
	s_branch .LBB0_952

; __device__ __forceinline__ unsigned cvt_pk_bf16(float lo, float hi) { const f32x2_t v = {lo, hi}; const bf16x2_t b = __builtin_convertvector(v, bf16x2_t); return __builtin_bit_cast(unsigned, b); }
; __device__ __forceinline__ unsigned cvt_pk_f16(float lo, float hi) { const f32x2 v = {lo, hi}; const h16x2_t h = __builtin_convertvector(v, h16x2_t); return __builtin_bit_cast(unsigned, h); }
; __device__ __forceinline__ u64 ssq_fix(float s) { return (u64)__float2ull_rn(s * 16777216.0f); }
; __device__ __forceinline__ void rows_to_bf16(const float* X, bf16_t* XB, bf16_t* X16, u64* ssq, int rows, int gw, int nw) {
;     int tid_ = threadIdx.x; asm volatile("" : "+v"(tid_)); asm volatile("" : "+v"(gw));
;     const int lane = tid_ & 63;
;     for (int r = gw; r < rows; r += nw) {
;         const float* xr = X + (size_t)r * D; bf16_t* br = XB + (size_t)r * D; float ss = 0.f;
; #pragma unroll
;         for (int i = 0; i < 8; ++i) {
;             const f32x4 v = *(const f32x4*)(xr + (i * 64 + lane) * 4);
;             ss += v[0] * v[0] + v[1] * v[1] + v[2] * v[2] + v[3] * v[3];
;             u32x2 w; w.x = cvt_pk_bf16(v[0], v[1]); w.y = cvt_pk_bf16(v[2], v[3]);
;             *(u32x2*)(br + (i * 64 + lane) * 4) = w;
;             if (X16) { u32x2 hq; hq.x = cvt_pk_f16(v[0], v[1]); hq.y = cvt_pk_f16(v[2], v[3]); *(u32x2*)(X16 + (size_t)r * D + (i * 64 + lane) * 4) = hq; }
;         }
;         ss = wave_sum(ss);
;         if (lane == 0) ssq[r] = ssq_fix(ss);
;     }
.LBB0_958:
	s_waitcnt lgkmcnt(0)
	global_load_dwordx4 v[14:17], v[6:7], off offset:-4096
	global_load_dwordx4 v[58:61], v[6:7], off offset:-3072
	global_load_dwordx4 v[62:65], v[6:7], off offset:-2048
	global_load_dwordx4 v[66:69], v[6:7], off offset:-1024
	global_load_dwordx4 v[70:73], v[6:7], off
	global_load_dwordx4 v[74:77], v[6:7], off offset:1024
	global_load_dwordx4 v[78:81], v[6:7], off offset:2048
	global_load_dwordx4 v[82:85], v[6:7], off offset:3072
	v_lshl_add_u64 v[18:19], s[22:23], 0, v[4:5]
	s_mov_b32 s2, 0x15a29000
	s_waitcnt vmcnt(18)
	v_add_co_u32_e32 v46, vcc, s2, v18
	s_waitcnt vmcnt(7)
	v_cvt_pk_bf16_f32 v18, v14, v15
	v_addc_co_u32_e32 v47, vcc, 0, v19, vcc
	v_cvt_pk_bf16_f32 v19, v16, v17
	global_store_dwordx2 v[46:47], v[18:19], off
	s_waitcnt vmcnt(7)
	s_nop 1
	v_mov_b64_e32 v[18:19], v[58:59]
	v_mov_b64_e32 v[20:21], v[60:61]
	v_mul_f32_e32 v1, v15, v15
	v_fmac_f32_e32 v1, v14, v14
	v_fmac_f32_e32 v1, v16, v16
	v_fmac_f32_e32 v1, v17, v17
	v_cvt_pk_bf16_f32 v22, v18, v19
	v_cvt_pk_bf16_f32 v23, v20, v21
	global_store_dwordx2 v[46:47], v[22:23], off offset:512
	s_waitcnt vmcnt(7)
	s_nop 1
	v_mov_b64_e32 v[22:23], v[62:63]
	v_mov_b64_e32 v[24:25], v[64:65]
	v_mul_f32_e32 v14, v19, v19
	v_fmac_f32_e32 v14, v18, v18
	v_fmac_f32_e32 v14, v20, v20
	v_fmac_f32_e32 v14, v21, v21
	v_add_f32_e32 v1, v1, v14
	v_cvt_pk_bf16_f32 v26, v22, v23
	v_cvt_pk_bf16_f32 v27, v24, v25
	global_store_dwordx2 v[46:47], v[26:27], off offset:1024
	s_waitcnt vmcnt(7)
	s_nop 1
	v_mov_b64_e32 v[26:27], v[66:67]
	v_mov_b64_e32 v[28:29], v[68:69]
	v_mul_f32_e32 v14, v23, v23
	v_fmac_f32_e32 v14, v22, v22
	v_fmac_f32_e32 v14, v24, v24
	v_fmac_f32_e32 v14, v25, v25
	v_add_f32_e32 v1, v1, v14
	v_cvt_pk_bf16_f32 v30, v26, v27
	v_cvt_pk_bf16_f32 v31, v28, v29
	global_store_dwordx2 v[46:47], v[30:31], off offset:1536
	s_waitcnt vmcnt(7)
	s_nop 1
	v_mov_b64_e32 v[30:31], v[70:71]
	v_mov_b64_e32 v[32:33], v[72:73]
	v_mul_f32_e32 v14, v27, v27
	v_fmac_f32_e32 v14, v26, v26
	v_fmac_f32_e32 v14, v28, v28
	v_fmac_f32_e32 v14, v29, v29
	v_add_f32_e32 v1, v1, v14
	v_cvt_pk_bf16_f32 v34, v30, v31
	v_cvt_pk_bf16_f32 v35, v32, v33
	global_store_dwordx2 v[46:47], v[34:35], off offset:2048
	s_waitcnt vmcnt(7)
	s_nop 1
	v_mov_b64_e32 v[34:35], v[74:75]
	v_mov_b64_e32 v[36:37], v[76:77]
	v_mul_f32_e32 v14, v31, v31
	v_fmac_f32_e32 v14, v30, v30
	v_fmac_f32_e32 v14, v32, v32
	v_fmac_f32_e32 v14, v33, v33
	v_add_f32_e32 v1, v1, v14
	v_cvt_pk_bf16_f32 v38, v34, v35
	v_cvt_pk_bf16_f32 v39, v36, v37
	global_store_dwordx2 v[46:47], v[38:39], off offset:2560
	s_waitcnt vmcnt(7)
	s_nop 1
	v_mov_b64_e32 v[38:39], v[78:79]
	v_mov_b64_e32 v[40:41], v[80:81]
	v_mul_f32_e32 v14, v35, v35
	v_fmac_f32_e32 v14, v34, v34
	v_fmac_f32_e32 v14, v36, v36
	v_fmac_f32_e32 v14, v37, v37
	v_add_f32_e32 v1, v1, v14
	v_cvt_pk_bf16_f32 v42, v38, v39
	v_cvt_pk_bf16_f32 v43, v40, v41
	global_store_dwordx2 v[46:47], v[42:43], off offset:3072
	s_waitcnt vmcnt(7)
	s_nop 1
	v_mov_b64_e32 v[42:43], v[82:83]
	v_mov_b64_e32 v[44:45], v[84:85]
	v_mul_f32_e32 v14, v39, v39
	v_fmac_f32_e32 v14, v38, v38
	v_fmac_f32_e32 v14, v40, v40
	v_fmac_f32_e32 v14, v41, v41
	v_add_f32_e32 v1, v1, v14
	v_mul_f32_e32 v14, v43, v43
	v_fmac_f32_e32 v14, v42, v42
	v_fmac_f32_e32 v14, v44, v44
	v_fmac_f32_e32 v14, v45, v45
	v_add_f32_e32 v1, v1, v14
	ds_bpermute_b32 v14, v8, v1
	v_cvt_pk_bf16_f32 v16, v42, v43
	v_cvt_pk_bf16_f32 v17, v44, v45
	global_store_dwordx2 v[46:47], v[16:17], off offset:3584
	s_waitcnt lgkmcnt(0)
	v_add_f32_e32 v1, v1, v14
	ds_bpermute_b32 v14, v9, v1
	s_waitcnt lgkmcnt(0)
	v_add_f32_e32 v1, v1, v14
	ds_bpermute_b32 v14, v12, v1
	s_waitcnt lgkmcnt(0)
	v_add_f32_e32 v1, v1, v14
	ds_bpermute_b32 v14, v11, v1
	s_waitcnt lgkmcnt(0)
	v_add_f32_e32 v1, v1, v14
	ds_bpermute_b32 v14, v10, v1
	s_waitcnt lgkmcnt(0)
	v_add_f32_e32 v1, v1, v14
	ds_bpermute_b32 v14, v13, v1
	s_and_saveexec_b64 s[2:3], s[4:5]
	s_cbranch_execz .LBB0_957
	s_waitcnt lgkmcnt(0)
	v_add_f32_e32 v1, v1, v14
	v_mul_f32_e32 v1, 0x4b800000, v1
	v_rndne_f32_e32 v1, v1
	v_mul_f32_e32 v14, 0x2f800000, v1
	v_floor_f32_e32 v15, v14
	v_fmac_f32_e32 v1, 0xcf800000, v15
	v_cvt_u32_f32_e32 v14, v1
	v_cvt_u32_f32_e32 v15, v15
	v_lshl_add_u64 v[16:17], s[22:23], 0, v[2:3]
	global_store_dwordx2 v[16:17], v[14:15], off
	s_branch .LBB0_957

; __device__ __forceinline__ f32x2 unpk_f16(unsigned u) { const h16x2_t h = __builtin_bit_cast(h16x2_t, u); return __builtin_convertvector(h, f32x2); }
; __device__ __forceinline__ float rstd_of(u64 ssq) { return frsq((float)ssq * (1.0f / (2048.0f * 16777216.0f)) + EPS); }
; __global__ void __launch_bounds__(NTHREADS, 2) fwd_kernel(Args a) {
;     ...
;         if (ph == 2 * NPL) {
;             const u64* ssq = ssq_all + (size_t)8 * T; const float* fg = AIN(27);
;             const int lane = tid & 63, gw = bx * 8 + (tid >> 6), nw = G * 8;
;             for (int r = gw; r < T; r += nw) {
;                 const float rs = rstd_of(ssq[r]); const bf16_t* hr = (const bf16_t*)(ws + WS_H16) + (size_t)r * D; float* orow = out + (size_t)r * D;
; #pragma unroll
;                 for (int i = 0; i < 8; ++i) { const int cidx = (i * 64 + lane) * 4; const u32x2 hw = *(const u32x2*)(hr + cidx); const f32x4 gg = *(const f32x4*)(fg + cidx);
;                     const f32x2 a2 = unpk_f16(hw.x), b2 = unpk_f16(hw.y); f32x4 v; v[0] = a2.x; v[1] = a2.y; v[2] = b2.x; v[3] = b2.y; *(f32x4*)(orow + cidx) = v * rs * gg; }
;             }
.LBB0_964:
	global_load_dwordx2 v[22:23], v[10:11], off
	global_load_dwordx2 v[24:25], v[14:15], off offset:-2048
	global_load_dwordx4 v[18:21], v[0:1], off
	global_load_dwordx2 v[58:59], v[14:15], off offset:-1536
	global_load_dwordx4 v[60:63], v[0:1], off offset:1024
	global_load_dwordx2 v[64:65], v[14:15], off offset:-1024
	global_load_dwordx4 v[66:69], v[0:1], off offset:2048
	global_load_dwordx2 v[70:71], v[14:15], off offset:-512
	global_load_dwordx4 v[72:75], v[0:1], off offset:3072
	global_load_dwordx2 v[76:77], v[14:15], off
	global_load_dwordx4 v[78:81], v[2:3], off
	global_load_dwordx2 v[82:83], v[14:15], off offset:512
	global_load_dwordx4 v[84:87], v[4:5], off
	global_load_dwordx2 v[88:89], v[14:15], off offset:1024
	global_load_dwordx4 v[90:93], v[6:7], off
	global_load_dwordx2 v[94:95], v[14:15], off offset:1536
	global_load_dwordx4 v[96:99], v[8:9], off
	s_movk_i32 s2, 0xf000
	v_add_co_u32_e32 v26, vcc, s2, v12
	v_add_u32_e32 v16, s6, v16
	s_nop 0
	v_addc_co_u32_e32 v27, vcc, -1, v13, vcc
	v_cmp_lt_i32_e32 vcc, s36, v16
	v_lshl_add_u64 v[10:11], v[10:11], 0, s[8:9]
	s_or_b64 s[14:15], vcc, s[14:15]
	s_waitcnt vmcnt(16)
	v_ffbh_u32_e32 v17, v23
	v_min_u32_e32 v17, 32, v17
	v_lshlrev_b64 v[22:23], v17, v[22:23]
	v_min_u32_e32 v22, 1, v22
	v_or_b32_e32 v22, v23, v22
	v_cvt_f32_u32_e32 v22, v22
	v_sub_u32_e32 v17, 32, v17
	s_waitcnt vmcnt(15)
	v_cvt_f32_f16_sdwa v29, v24 dst_sel:DWORD dst_unused:UNUSED_PAD src0_sel:WORD_1
	v_cvt_f32_f16_e32 v28, v24
	v_ldexp_f32 v17, v22, v17
	v_fmamk_f32 v17, v17, 0x2e000000, v239
	v_cvt_f32_f16_sdwa v31, v25 dst_sel:DWORD dst_unused:UNUSED_PAD src0_sel:WORD_1
	v_cvt_f32_f16_e32 v30, v25
	v_rsq_f32_e32 v22, v17
	s_nop 0
	v_pk_mul_f32 v[24:25], v[22:23], v[28:29] op_sel_hi:[0,1]
	v_pk_mul_f32 v[28:29], v[22:23], v[30:31] op_sel_hi:[0,1]
	s_waitcnt vmcnt(14)
	v_pk_mul_f32 v[20:21], v[20:21], v[28:29]
	v_pk_mul_f32 v[18:19], v[18:19], v[24:25]
	global_store_dwordx4 v[26:27], v[18:21], off offset:-3072
	s_waitcnt vmcnt(14)
	s_nop 1
	v_mov_b64_e32 v[24:25], v[58:59]
	s_nop 0
	s_waitcnt vmcnt(13)
	s_nop 1
	v_mov_b64_e32 v[18:19], v[60:61]
	v_mov_b64_e32 v[20:21], v[62:63]
	v_cvt_f32_f16_sdwa v29, v24 dst_sel:DWORD dst_unused:UNUSED_PAD src0_sel:WORD_1
	v_cvt_f32_f16_e32 v28, v24
	v_cvt_f32_f16_sdwa v31, v25 dst_sel:DWORD dst_unused:UNUSED_PAD src0_sel:WORD_1
	v_cvt_f32_f16_e32 v30, v25
	v_pk_mul_f32 v[24:25], v[22:23], v[28:29] op_sel_hi:[0,1]
	v_pk_mul_f32 v[18:19], v[18:19], v[24:25]
	v_pk_mul_f32 v[28:29], v[22:23], v[30:31] op_sel_hi:[0,1]
	v_pk_mul_f32 v[20:21], v[20:21], v[28:29]
	global_store_dwordx4 v[26:27], v[18:21], off offset:-2048
	s_waitcnt vmcnt(13)
	s_nop 1
	v_mov_b64_e32 v[24:25], v[64:65]
	s_nop 0
	s_waitcnt vmcnt(12)
	s_nop 1
	v_mov_b64_e32 v[18:19], v[66:67]
	v_mov_b64_e32 v[20:21], v[68:69]
	v_cvt_f32_f16_sdwa v29, v24 dst_sel:DWORD dst_unused:UNUSED_PAD src0_sel:WORD_1
	v_cvt_f32_f16_e32 v28, v24
	v_cvt_f32_f16_sdwa v31, v25 dst_sel:DWORD dst_unused:UNUSED_PAD src0_sel:WORD_1
	v_cvt_f32_f16_e32 v30, v25
	v_pk_mul_f32 v[24:25], v[22:23], v[28:29] op_sel_hi:[0,1]
	v_pk_mul_f32 v[18:19], v[18:19], v[24:25]
	v_pk_mul_f32 v[28:29], v[22:23], v[30:31] op_sel_hi:[0,1]
	v_pk_mul_f32 v[20:21], v[20:21], v[28:29]
	global_store_dwordx4 v[26:27], v[18:21], off offset:-1024
	s_waitcnt vmcnt(12)
	s_nop 1
	v_mov_b64_e32 v[24:25], v[70:71]
	s_nop 0
	s_waitcnt vmcnt(11)
	s_nop 1
	v_mov_b64_e32 v[18:19], v[72:73]
	v_mov_b64_e32 v[20:21], v[74:75]
	v_cvt_f32_f16_sdwa v27, v24 dst_sel:DWORD dst_unused:UNUSED_PAD src0_sel:WORD_1
	v_cvt_f32_f16_e32 v26, v24
	v_cvt_f32_f16_sdwa v29, v25 dst_sel:DWORD dst_unused:UNUSED_PAD src0_sel:WORD_1
	v_cvt_f32_f16_e32 v28, v25
	v_pk_mul_f32 v[24:25], v[22:23], v[26:27] op_sel_hi:[0,1]
	v_pk_mul_f32 v[18:19], v[18:19], v[24:25]
	v_pk_mul_f32 v[26:27], v[22:23], v[28:29] op_sel_hi:[0,1]
	v_pk_mul_f32 v[20:21], v[20:21], v[26:27]
	global_store_dwordx4 v[12:13], v[18:21], off offset:-4096
	s_waitcnt vmcnt(11)
	s_nop 1
	v_mov_b64_e32 v[24:25], v[76:77]
	s_nop 0
	s_waitcnt vmcnt(10)
	s_nop 1
	v_mov_b64_e32 v[18:19], v[78:79]
	v_mov_b64_e32 v[20:21], v[80:81]
	v_cvt_f32_f16_sdwa v27, v24 dst_sel:DWORD dst_unused:UNUSED_PAD src0_sel:WORD_1
	v_cvt_f32_f16_e32 v26, v24
	v_cvt_f32_f16_sdwa v29, v25 dst_sel:DWORD dst_unused:UNUSED_PAD src0_sel:WORD_1
	v_cvt_f32_f16_e32 v28, v25
	v_pk_mul_f32 v[24:25], v[22:23], v[26:27] op_sel_hi:[0,1]
	v_pk_mul_f32 v[18:19], v[18:19], v[24:25]
	v_pk_mul_f32 v[26:27], v[22:23], v[28:29] op_sel_hi:[0,1]
	v_pk_mul_f32 v[20:21], v[20:21], v[26:27]
	global_store_dwordx4 v[12:13], v[18:21], off offset:-3072
	s_waitcnt vmcnt(10)
	s_nop 1
	v_mov_b64_e32 v[24:25], v[82:83]
	s_nop 0
	s_waitcnt vmcnt(9)
	s_nop 1
	v_mov_b64_e32 v[18:19], v[84:85]
	v_mov_b64_e32 v[20:21], v[86:87]
	v_cvt_f32_f16_sdwa v27, v24 dst_sel:DWORD dst_unused:UNUSED_PAD src0_sel:WORD_1
	v_cvt_f32_f16_e32 v26, v24
	v_cvt_f32_f16_sdwa v29, v25 dst_sel:DWORD dst_unused:UNUSED_PAD src0_sel:WORD_1
	v_cvt_f32_f16_e32 v28, v25
	v_pk_mul_f32 v[24:25], v[22:23], v[26:27] op_sel_hi:[0,1]
	v_pk_mul_f32 v[18:19], v[18:19], v[24:25]
	v_pk_mul_f32 v[26:27], v[22:23], v[28:29] op_sel_hi:[0,1]
	v_pk_mul_f32 v[20:21], v[20:21], v[26:27]
	global_store_dwordx4 v[12:13], v[18:21], off offset:-2048
	s_waitcnt vmcnt(9)
	s_nop 1
	v_mov_b64_e32 v[24:25], v[88:89]
	s_nop 0
	s_waitcnt vmcnt(8)
	s_nop 1
	v_mov_b64_e32 v[18:19], v[90:91]
	v_mov_b64_e32 v[20:21], v[92:93]
	v_cvt_f32_f16_sdwa v27, v24 dst_sel:DWORD dst_unused:UNUSED_PAD src0_sel:WORD_1
	v_cvt_f32_f16_e32 v26, v24
	v_cvt_f32_f16_sdwa v29, v25 dst_sel:DWORD dst_unused:UNUSED_PAD src0_sel:WORD_1
	v_cvt_f32_f16_e32 v28, v25
	v_pk_mul_f32 v[24:25], v[22:23], v[26:27] op_sel_hi:[0,1]
	v_pk_mul_f32 v[18:19], v[18:19], v[24:25]
	v_pk_mul_f32 v[26:27], v[22:23], v[28:29] op_sel_hi:[0,1]
	v_pk_mul_f32 v[20:21], v[20:21], v[26:27]
	global_store_dwordx4 v[12:13], v[18:21], off offset:-1024
	s_waitcnt vmcnt(8)
	s_nop 1
	v_mov_b64_e32 v[24:25], v[94:95]
	s_nop 0
	s_waitcnt vmcnt(7)
	s_nop 1
	v_mov_b64_e32 v[18:19], v[96:97]
	v_mov_b64_e32 v[20:21], v[98:99]
	v_lshl_add_u64 v[14:15], v[14:15], 0, s[12:13]
	v_cvt_f32_f16_sdwa v27, v24 dst_sel:DWORD dst_unused:UNUSED_PAD src0_sel:WORD_1
	v_cvt_f32_f16_e32 v26, v24
	v_cvt_f32_f16_sdwa v29, v25 dst_sel:DWORD dst_unused:UNUSED_PAD src0_sel:WORD_1
	v_cvt_f32_f16_e32 v28, v25
	v_pk_mul_f32 v[24:25], v[22:23], v[26:27] op_sel_hi:[0,1]
	v_pk_mul_f32 v[18:19], v[18:19], v[24:25]
	v_pk_mul_f32 v[22:23], v[22:23], v[28:29] op_sel_hi:[0,1]
	v_pk_mul_f32 v[20:21], v[20:21], v[22:23]
	global_store_dwordx4 v[12:13], v[18:21], off
	v_lshl_add_u64 v[12:13], v[12:13], 0, s[10:11]
	s_andn2_b64 exec, exec, s[14:15]
	s_cbranch_execnz .LBB0_964

; #define LAS __attribute__((address_space(3)))
; __device__ __forceinline__ unsigned xb_xcc_id() { return (unsigned)__builtin_amdgcn_s_getreg((3 << 11) | 20) & 0xFu; }
; __device__ __forceinline__ void xcd_barrier(unsigned* bar, volatile LAS unsigned* st, bool tid0, unsigned G) {
;     asm volatile("s_waitcnt vmcnt(0)" ::: "memory");
;     __syncthreads();
;     if (tid0) {
;         const unsigned x = xb_xcc_id();
;         __builtin_amdgcn_s_waitcnt(0);
;         unsigned nloc = st[0], nx = st[1];
;         if (nloc == 0u) { xcd_barrier_complete(bar, x, G, nloc, nx); st[0] = nloc; st[1] = nx; }
; __global__ void __launch_bounds__(NTHREADS, 2) fwd_kernel(Args a) {
;     ...
;         if (vp + 1 < ph_hi + NVP) {
;             if (vp == ph_lo) cg::this_grid().sync();
;             else xcd_barrier((unsigned*)(ws + WS_CTL + CTL_BAR), xb_st, tid == 0, (unsigned)G);
.LBB0_966:
	s_waitcnt vmcnt(0)
	v_cmp_eq_u32_e32 vcc, 0, v244
	s_waitcnt lgkmcnt(0)
	s_barrier
	s_and_saveexec_b64 s[4:5], vcc
	s_cbranch_execz .LBB0_1019
	v_readlane_b32 s3, v255, 7
	s_getreg_b32 s2, hwreg(HW_REG_XCC_ID, 0, 4)
	s_waitcnt vmcnt(0) expcnt(0) lgkmcnt(0)
	v_mov_b32_e32 v0, s3
	ds_read_b32 v2, v0
	v_readlane_b32 s3, v255, 8
	s_and_b32 s38, s2, 15
	s_waitcnt lgkmcnt(0)
	v_cmp_ne_u32_e32 vcc, 0, v2
	v_mov_b32_e32 v0, s3
	ds_read_b32 v0, v0
	s_cbranch_vccnz .LBB0_983
	s_add_u32 s6, s22, 0xd901200
	s_addc_u32 s7, s23, 0
	s_add_u32 s8, s22, 0xd901400
	s_addc_u32 s9, s23, 0
	s_add_u32 s10, s22, 0xd901500
	s_addc_u32 s11, s23, 0
	s_add_u32 s12, s22, 0xd901600
	s_addc_u32 s13, s23, 0
	s_add_u32 s14, s22, 0xd901700
	s_addc_u32 s15, s23, 0
	s_add_u32 s16, s22, 0xd901800
	s_addc_u32 s17, s23, 0
	s_add_u32 s18, s22, 0xd901900
	s_addc_u32 s19, s23, 0
	s_add_u32 s20, s22, 0xd901a00
	s_addc_u32 s21, s23, 0
	s_add_u32 s24, s22, 0xd901b00
	s_addc_u32 s25, s23, 0
	s_add_u32 s30, s22, 0xd901c00
	s_addc_u32 s31, s23, 0
	s_add_u32 s52, s22, 0xd901d00
	s_addc_u32 s53, s23, 0
	s_add_u32 s54, s22, 0xd901e00
	s_addc_u32 s55, s23, 0
	s_add_u32 s60, s22, 0xd901f00
	s_addc_u32 s61, s23, 0
	s_add_u32 s62, s22, 0xd902000
	s_addc_u32 s63, s23, 0
	s_add_u32 s64, s22, 0xd902100
	s_addc_u32 s65, s23, 0
	s_add_u32 s66, s22, 0xd902200
	s_addc_u32 s67, s23, 0
	s_add_u32 s72, s22, 0xd902300
	s_addc_u32 s73, s23, 0
	s_mov_b32 s39, 1
	s_branch .LBB0_971
